# GEMM unit preheaders: the 127 accumulator-clearing v_mov_b32 per unit paired into 63 v_mov_b64 (8 of the 9 GEMM instances)
# speedup vs baseline: 1.0058x; 1.0058x over previous
; template <class Epi, class Sched, bool ALIGN_EPI = false, bool SP2 = false>
; __device__ __forceinline__ void gemm_phase(PG8_LAS unsigned char* lds, const Gemm g, const Sched& S, const Epi& E, const int wid) {
;     ...
;         const char* nA = has_next ? (const char*)g.A + (size_t)nxt.pm * tstep : cA; const char* nB = has_next ? (const char*)g.Bt + (size_t)nxt.pn * tstep : cB;
;         for (int t = 0; t < nt; t += 2) {
;             const bool last = (t == nt - 2);
;             const char* a1 = cA + (size_t)(t + 1) * kstep;
;             const char* a2 = last ? nA : cA + (size_t)(t + 2) * kstep; const char* b2 = last ? nB : cB + (size_t)(t + 2) * kstep;
;     ...
; #pragma unroll
;         for (int a = 0; a < 2; ++a)
; #pragma unroll
;             for (int b = 0; b < 2; ++b)
; #pragma unroll
;                 for (int m = 0; m < 4; ++m)
; #pragma unroll
;                     for (int n = 0; n < 2; ++n) acc[a][b][m][n] = (f32x4){0.f, 0.f, 0.f, 0.f};
.LBB0_276:
	s_ashr_i32 s53, s52, 31
	s_lshl_b64 s[54:55], s[52:53], 21
	s_add_u32 s54, s2, s54
	s_addc_u32 s55, s3, s55
	s_and_b64 s[56:57], s[4:5], exec
	s_cselect_b32 s53, s55, s61
	s_cselect_b32 s59, s54, s60
	s_ashr_i32 s51, s50, 31
	s_lshl_b64 s[56:57], s[50:51], 21
	s_add_u32 s56, s33, s56
	s_addc_u32 s57, s74, s57
	s_and_b64 s[66:67], s[4:5], exec
	s_cselect_b32 s51, s57, s63
	s_cselect_b32 s65, s56, s62
	s_add_u32 s60, s60, 0x100080
	s_addc_u32 s61, s61, 0
	s_add_u32 s68, s62, 0x100
	v_mov_b32_e32 v0, 0
	s_addc_u32 s69, s63, 0
	s_mov_b32 s70, -2
	v_mov_b32_e32 v1, v0
	v_mov_b64_e32 v[2:3], 0
	v_mov_b64_e32 v[4:5], 0
	v_mov_b64_e32 v[6:7], 0
	v_mov_b64_e32 v[16:17], 0
	v_mov_b64_e32 v[18:19], 0
	v_mov_b64_e32 v[20:21], 0
	v_mov_b64_e32 v[22:23], 0
	v_mov_b64_e32 v[32:33], 0
	v_mov_b64_e32 v[34:35], 0
	v_mov_b64_e32 v[36:37], 0
	v_mov_b64_e32 v[38:39], 0
	v_mov_b64_e32 v[48:49], 0
	v_mov_b64_e32 v[50:51], 0
	v_mov_b64_e32 v[52:53], 0
	v_mov_b64_e32 v[54:55], 0
	v_mov_b64_e32 v[8:9], 0
	v_mov_b64_e32 v[10:11], 0
	v_mov_b64_e32 v[12:13], 0
	v_mov_b64_e32 v[14:15], 0
	v_mov_b64_e32 v[24:25], 0
	v_mov_b64_e32 v[26:27], 0
	v_mov_b64_e32 v[28:29], 0
	v_mov_b64_e32 v[30:31], 0
	v_mov_b64_e32 v[40:41], 0
	v_mov_b64_e32 v[42:43], 0
	v_mov_b64_e32 v[44:45], 0
	v_mov_b64_e32 v[46:47], 0
	v_mov_b64_e32 v[56:57], 0
	v_mov_b64_e32 v[58:59], 0
	v_mov_b64_e32 v[60:61], 0
	v_mov_b64_e32 v[62:63], 0
	v_mov_b64_e32 v[64:65], 0
	v_mov_b64_e32 v[66:67], 0
	v_mov_b64_e32 v[68:69], 0
	v_mov_b64_e32 v[70:71], 0
	v_mov_b64_e32 v[80:81], 0
	v_mov_b64_e32 v[82:83], 0
	v_mov_b64_e32 v[84:85], 0
	v_mov_b64_e32 v[86:87], 0
	v_mov_b64_e32 v[96:97], 0
	v_mov_b64_e32 v[98:99], 0
	v_mov_b64_e32 v[100:101], 0
	v_mov_b64_e32 v[102:103], 0
	v_mov_b64_e32 v[112:113], 0
	v_mov_b64_e32 v[114:115], 0
	v_mov_b64_e32 v[116:117], 0
	v_mov_b64_e32 v[118:119], 0
	v_mov_b64_e32 v[72:73], 0
	v_mov_b64_e32 v[74:75], 0
	v_mov_b64_e32 v[76:77], 0
	v_mov_b64_e32 v[78:79], 0
	v_mov_b64_e32 v[88:89], 0
	v_mov_b64_e32 v[90:91], 0
	v_mov_b64_e32 v[92:93], 0
	v_mov_b64_e32 v[94:95], 0
	v_mov_b64_e32 v[104:105], 0
	v_mov_b64_e32 v[106:107], 0
	v_mov_b64_e32 v[108:109], 0
	v_mov_b64_e32 v[110:111], 0
	v_mov_b64_e32 v[120:121], 0
	v_mov_b64_e32 v[122:123], 0
	v_mov_b64_e32 v[124:125], 0
	v_mov_b64_e32 v[126:127], 0

;     DI bool next(int i, Unit& u) const { const int L = i * G + c; if (L >= 1536) return false; const int which = L >> 9, r = L & 511; u.pm = which * 64 + (r & 63); u.pn = which * 8 + (r >> 6); return true; }
;     DI bool next(int i, Unit& u) const { Unit t; if (!so.next(i >> 1, t)) return false; const int which = i & 1; u.pm = which * 64 + t.pm; u.pn = which * 16 + t.pn; return true; }
; template <class Epi, class Sched, bool ALIGN_EPI = false, bool SP2 = false>
; __device__ __forceinline__ void gemm_phase(PG8_LAS unsigned char* lds, const Gemm g, const Sched& S, const Epi& E, const int wid) {
;     ...
;     f32x4 acc[2][2][4][2];
; #pragma unroll
;     for (int a = 0; a < 2; ++a)
; #pragma unroll
;         for (int b = 0; b < 2; ++b)
; #pragma unroll
;             for (int m = 0; m < 4; ++m)
; #pragma unroll
;                 for (int n = 0; n < 2; ++n) acc[a][b][m][n] = (f32x4){0.f, 0.f, 0.f, 0.f};
;     ...
;     for (;;) {
;         const bool has_next = S.next(ui + 1, nxt);
;         const char* nA = has_next ? (const char*)g.A + (size_t)nxt.pm * tstep : cA; const char* nB = has_next ? (const char*)g.Bt + (size_t)nxt.pn * tstep : cB;
;         for (int t = 0; t < nt; t += 2) {
;             const bool last = (t == nt - 2);
;             const char* a1 = cA + (size_t)(t + 1) * kstep;
;             const char* a2 = last ? nA : cA + (size_t)(t + 2) * kstep; const char* b2 = last ? nB : cB + (size_t)(t + 2) * kstep;
;     ...
; #pragma unroll
;         for (int a = 0; a < 2; ++a)
; #pragma unroll
;             for (int b = 0; b < 2; ++b)
; #pragma unroll
;                 for (int m = 0; m < 4; ++m)
; #pragma unroll
;                     for (int n = 0; n < 2; ++n) acc[a][b][m][n] = (f32x4){0.f, 0.f, 0.f, 0.f};
.LBB0_2059:
	v_mov_b32_e32 v127, 0
	s_and_b64 vcc, exec, s[4:5]
	v_mov_b32_e32 v126, v127
	v_mov_b32_e32 v125, v127
	v_mov_b32_e32 v124, v127
	v_mov_b32_e32 v123, v127
	v_mov_b32_e32 v122, v127
	v_mov_b32_e32 v121, v127
	v_mov_b32_e32 v120, v127
	v_mov_b32_e32 v119, v127
	v_mov_b32_e32 v118, v127
	v_mov_b32_e32 v117, v127
	v_mov_b32_e32 v116, v127
	v_mov_b32_e32 v115, v127
	v_mov_b32_e32 v114, v127
	v_mov_b32_e32 v113, v127
	v_mov_b32_e32 v112, v127
	v_mov_b32_e32 v111, v127
	v_mov_b32_e32 v110, v127
	v_mov_b32_e32 v109, v127
	v_mov_b32_e32 v108, v127
	v_mov_b32_e32 v107, v127
	v_mov_b32_e32 v106, v127
	v_mov_b32_e32 v105, v127
	v_mov_b32_e32 v104, v127
	v_mov_b32_e32 v103, v127
	v_mov_b32_e32 v102, v127
	v_mov_b32_e32 v101, v127
	v_mov_b32_e32 v100, v127
	v_mov_b32_e32 v99, v127
	v_mov_b32_e32 v98, v127
	v_mov_b32_e32 v97, v127
	v_mov_b32_e32 v96, v127
	v_mov_b32_e32 v63, v127
	v_mov_b32_e32 v62, v127
	v_mov_b32_e32 v61, v127
	v_mov_b32_e32 v60, v127
	v_mov_b32_e32 v59, v127
	v_mov_b32_e32 v58, v127
	v_mov_b32_e32 v57, v127
	v_mov_b32_e32 v56, v127
	v_mov_b32_e32 v55, v127
	v_mov_b32_e32 v54, v127
	v_mov_b32_e32 v53, v127
	v_mov_b32_e32 v52, v127
	v_mov_b32_e32 v51, v127
	v_mov_b32_e32 v50, v127
	v_mov_b32_e32 v49, v127
	v_mov_b32_e32 v48, v127
	v_mov_b32_e32 v47, v127
	v_mov_b32_e32 v46, v127
	v_mov_b32_e32 v45, v127
	v_mov_b32_e32 v44, v127
	v_mov_b32_e32 v43, v127
	v_mov_b32_e32 v42, v127
	v_mov_b32_e32 v41, v127
	v_mov_b32_e32 v40, v127
	v_mov_b32_e32 v39, v127
	v_mov_b32_e32 v38, v127
	v_mov_b32_e32 v37, v127
	v_mov_b32_e32 v36, v127
	v_mov_b32_e32 v35, v127
	v_mov_b32_e32 v34, v127
	v_mov_b32_e32 v33, v127
	v_mov_b32_e32 v32, v127
	v_mov_b32_e32 v95, v127
	v_mov_b32_e32 v94, v127
	v_mov_b32_e32 v93, v127
	v_mov_b32_e32 v92, v127
	v_mov_b32_e32 v91, v127
	v_mov_b32_e32 v90, v127
	v_mov_b32_e32 v89, v127
	v_mov_b32_e32 v88, v127
	v_mov_b32_e32 v87, v127
	v_mov_b32_e32 v86, v127
	v_mov_b32_e32 v85, v127
	v_mov_b32_e32 v84, v127
	v_mov_b32_e32 v83, v127
	v_mov_b32_e32 v82, v127
	v_mov_b32_e32 v81, v127
	v_mov_b32_e32 v80, v127
	v_mov_b32_e32 v79, v127
	v_mov_b32_e32 v78, v127
	v_mov_b32_e32 v77, v127
	v_mov_b32_e32 v76, v127
	v_mov_b32_e32 v75, v127
	v_mov_b32_e32 v74, v127
	v_mov_b32_e32 v73, v127
	v_mov_b32_e32 v72, v127
	v_mov_b32_e32 v71, v127
	v_mov_b32_e32 v70, v127
	v_mov_b32_e32 v69, v127
	v_mov_b32_e32 v68, v127
	v_mov_b32_e32 v67, v127
	v_mov_b32_e32 v66, v127
	v_mov_b32_e32 v65, v127
	v_mov_b32_e32 v64, v127
	v_mov_b32_e32 v31, v127
	v_mov_b32_e32 v30, v127
	v_mov_b32_e32 v29, v127
	v_mov_b32_e32 v28, v127
	v_mov_b32_e32 v27, v127
	v_mov_b32_e32 v26, v127
	v_mov_b32_e32 v25, v127
	v_mov_b32_e32 v24, v127
	v_mov_b32_e32 v23, v127
	v_mov_b32_e32 v22, v127
	v_mov_b32_e32 v21, v127
	v_mov_b32_e32 v20, v127
	v_mov_b32_e32 v19, v127
	v_mov_b32_e32 v18, v127
	v_mov_b32_e32 v17, v127
	v_mov_b32_e32 v16, v127
	v_mov_b32_e32 v15, v127
	v_mov_b32_e32 v14, v127
	v_mov_b32_e32 v13, v127
	v_mov_b32_e32 v12, v127
	v_mov_b32_e32 v11, v127
	v_mov_b32_e32 v10, v127
	v_mov_b32_e32 v9, v127
	v_mov_b32_e32 v8, v127
	v_mov_b32_e32 v7, v127
	v_mov_b32_e32 v6, v127
	v_mov_b32_e32 v5, v127
	v_mov_b32_e32 v4, v127
	v_mov_b32_e32 v3, v127
	v_mov_b32_e32 v2, v127
	v_mov_b32_e32 v1, v127
	v_mov_b32_e32 v0, v127
	s_cbranch_vccnz .LBB0_2062
	s_add_u32 s0, s0, 0x80
	s_addc_u32 s1, s1, 0
	s_add_u32 s8, s2, 0x100
	v_mov_b32_e32 v0, 0
	s_addc_u32 s9, s3, 0
	s_mov_b32 s2, 0
	v_mov_b32_e32 v1, v0
	v_mov_b64_e32 v[2:3], 0
	v_mov_b64_e32 v[4:5], 0
	v_mov_b64_e32 v[6:7], 0
	v_mov_b64_e32 v[8:9], 0
	v_mov_b64_e32 v[10:11], 0
	v_mov_b64_e32 v[12:13], 0
	v_mov_b64_e32 v[14:15], 0
	v_mov_b64_e32 v[16:17], 0
	v_mov_b64_e32 v[18:19], 0
	v_mov_b64_e32 v[20:21], 0
	v_mov_b64_e32 v[22:23], 0
	v_mov_b64_e32 v[24:25], 0
	v_mov_b64_e32 v[26:27], 0
	v_mov_b64_e32 v[28:29], 0
	v_mov_b64_e32 v[30:31], 0
	v_mov_b64_e32 v[64:65], 0
	v_mov_b64_e32 v[66:67], 0
	v_mov_b64_e32 v[68:69], 0
	v_mov_b64_e32 v[70:71], 0
	v_mov_b64_e32 v[72:73], 0
	v_mov_b64_e32 v[74:75], 0
	v_mov_b64_e32 v[76:77], 0
	v_mov_b64_e32 v[78:79], 0
	v_mov_b64_e32 v[80:81], 0
	v_mov_b64_e32 v[82:83], 0
	v_mov_b64_e32 v[84:85], 0
	v_mov_b64_e32 v[86:87], 0
	v_mov_b64_e32 v[88:89], 0
	v_mov_b64_e32 v[90:91], 0
	v_mov_b64_e32 v[92:93], 0
	v_mov_b64_e32 v[94:95], 0
	v_mov_b64_e32 v[32:33], 0
	v_mov_b64_e32 v[34:35], 0
	v_mov_b64_e32 v[36:37], 0
	v_mov_b64_e32 v[38:39], 0
	v_mov_b64_e32 v[40:41], 0
	v_mov_b64_e32 v[42:43], 0
	v_mov_b64_e32 v[44:45], 0
	v_mov_b64_e32 v[46:47], 0
	v_mov_b64_e32 v[48:49], 0
	v_mov_b64_e32 v[50:51], 0
	v_mov_b64_e32 v[52:53], 0
	v_mov_b64_e32 v[54:55], 0
	v_mov_b64_e32 v[56:57], 0
	v_mov_b64_e32 v[58:59], 0
	v_mov_b64_e32 v[60:61], 0
	v_mov_b64_e32 v[62:63], 0
	v_mov_b64_e32 v[96:97], 0
	v_mov_b64_e32 v[98:99], 0
	v_mov_b64_e32 v[100:101], 0
	v_mov_b64_e32 v[102:103], 0
	v_mov_b64_e32 v[104:105], 0
	v_mov_b64_e32 v[106:107], 0
	v_mov_b64_e32 v[108:109], 0
	v_mov_b64_e32 v[110:111], 0
	v_mov_b64_e32 v[112:113], 0
	v_mov_b64_e32 v[114:115], 0
	v_mov_b64_e32 v[116:117], 0
	v_mov_b64_e32 v[118:119], 0
	v_mov_b64_e32 v[120:121], 0
	v_mov_b64_e32 v[122:123], 0
	v_mov_b64_e32 v[124:125], 0
	v_mov_b64_e32 v[126:127], 0

; template <class Epi, class Sched, bool ALIGN_EPI = false, bool SP2 = false>
; __device__ __forceinline__ void gemm_phase(PG8_LAS unsigned char* lds, const Gemm g, const Sched& S, const Epi& E, const int wid) {
;     ...
;         const char* nA = has_next ? (const char*)g.A + (size_t)nxt.pm * tstep : cA; const char* nB = has_next ? (const char*)g.Bt + (size_t)nxt.pn * tstep : cB;
;         for (int t = 0; t < nt; t += 2) {
;             const bool last = (t == nt - 2);
;             const char* a1 = cA + (size_t)(t + 1) * kstep;
;             const char* a2 = last ? nA : cA + (size_t)(t + 2) * kstep; const char* b2 = last ? nB : cB + (size_t)(t + 2) * kstep;
;     ...
; #pragma unroll
;         for (int a = 0; a < 2; ++a)
; #pragma unroll
;             for (int b = 0; b < 2; ++b)
; #pragma unroll
;                 for (int m = 0; m < 4; ++m)
; #pragma unroll
;                     for (int n = 0; n < 2; ++n) acc[a][b][m][n] = (f32x4){0.f, 0.f, 0.f, 0.f};
.LBB0_2716:
	s_ashr_i32 s21, s20, 31
	s_lshl_b64 s[22:23], s[20:21], 21
	s_add_u32 s22, s33, s22
	s_addc_u32 s23, s36, s23
	s_and_b64 s[24:25], s[4:5], exec
	s_cselect_b32 s1, s23, s29
	s_cselect_b32 s21, s22, s28
	s_ashr_i32 s19, s18, 31
	s_lshl_b64 s[24:25], s[18:19], 21
	s_add_u32 s24, s37, s24
	s_addc_u32 s25, s38, s25
	s_and_b64 s[34:35], s[4:5], exec
	s_cselect_b32 s19, s25, s31
	s_cselect_b32 s52, s24, s30
	s_add_u32 s28, s28, 0x100080
	s_addc_u32 s29, s29, 0
	s_add_u32 s53, s30, 0x100
	v_mov_b32_e32 v0, 0
	s_addc_u32 s54, s31, 0
	s_mov_b32 s55, -2
	s_waitcnt lgkmcnt(0)
	v_mov_b32_e32 v1, v0
	v_mov_b64_e32 v[2:3], 0
	v_mov_b64_e32 v[4:5], 0
	v_mov_b64_e32 v[6:7], 0
	v_mov_b64_e32 v[16:17], 0
	v_mov_b64_e32 v[18:19], 0
	v_mov_b64_e32 v[20:21], 0
	v_mov_b64_e32 v[22:23], 0
	v_mov_b64_e32 v[32:33], 0
	v_mov_b64_e32 v[34:35], 0
	v_mov_b64_e32 v[36:37], 0
	v_mov_b64_e32 v[38:39], 0
	v_mov_b64_e32 v[48:49], 0
	v_mov_b64_e32 v[50:51], 0
	v_mov_b64_e32 v[52:53], 0
	v_mov_b64_e32 v[54:55], 0
	v_mov_b64_e32 v[8:9], 0
	v_mov_b64_e32 v[10:11], 0
	v_mov_b64_e32 v[12:13], 0
	v_mov_b64_e32 v[14:15], 0
	v_mov_b64_e32 v[24:25], 0
	v_mov_b64_e32 v[26:27], 0
	v_mov_b64_e32 v[28:29], 0
	v_mov_b64_e32 v[30:31], 0
	v_mov_b64_e32 v[40:41], 0
	v_mov_b64_e32 v[42:43], 0
	v_mov_b64_e32 v[44:45], 0
	v_mov_b64_e32 v[46:47], 0
	v_mov_b64_e32 v[56:57], 0
	v_mov_b64_e32 v[58:59], 0
	v_mov_b64_e32 v[60:61], 0
	v_mov_b64_e32 v[62:63], 0
	v_mov_b64_e32 v[64:65], 0
	v_mov_b64_e32 v[66:67], 0
	v_mov_b64_e32 v[68:69], 0
	v_mov_b64_e32 v[70:71], 0
	v_mov_b64_e32 v[80:81], 0
	v_mov_b64_e32 v[82:83], 0
	v_mov_b64_e32 v[84:85], 0
	v_mov_b64_e32 v[86:87], 0
	v_mov_b64_e32 v[96:97], 0
	v_mov_b64_e32 v[98:99], 0
	v_mov_b64_e32 v[100:101], 0
	v_mov_b64_e32 v[102:103], 0
	v_mov_b64_e32 v[112:113], 0
	v_mov_b64_e32 v[114:115], 0
	v_mov_b64_e32 v[116:117], 0
	v_mov_b64_e32 v[118:119], 0
	v_mov_b64_e32 v[72:73], 0
	v_mov_b64_e32 v[74:75], 0
	v_mov_b64_e32 v[76:77], 0
	v_mov_b64_e32 v[78:79], 0
	v_mov_b64_e32 v[88:89], 0
	v_mov_b64_e32 v[90:91], 0
	v_mov_b64_e32 v[92:93], 0
	v_mov_b64_e32 v[94:95], 0
	v_mov_b64_e32 v[104:105], 0
	v_mov_b64_e32 v[106:107], 0
	v_mov_b64_e32 v[108:109], 0
	v_mov_b64_e32 v[110:111], 0
	v_mov_b64_e32 v[120:121], 0
	v_mov_b64_e32 v[122:123], 0
	v_mov_b64_e32 v[124:125], 0
	v_mov_b64_e32 v[126:127], 0

; template <class Epi, class Sched, bool ALIGN_EPI = false, bool SP2 = false>
; __device__ __forceinline__ void gemm_phase(PG8_LAS unsigned char* lds, const Gemm g, const Sched& S, const Epi& E, const int wid) {
;     ...
;         const char* nA = has_next ? (const char*)g.A + (size_t)nxt.pm * tstep : cA; const char* nB = has_next ? (const char*)g.Bt + (size_t)nxt.pn * tstep : cB;
;         for (int t = 0; t < nt; t += 2) {
;             const bool last = (t == nt - 2);
;             const char* a1 = cA + (size_t)(t + 1) * kstep;
;             const char* a2 = last ? nA : cA + (size_t)(t + 2) * kstep; const char* b2 = last ? nB : cB + (size_t)(t + 2) * kstep;
;     ...
; #pragma unroll
;         for (int a = 0; a < 2; ++a)
; #pragma unroll
;             for (int b = 0; b < 2; ++b)
; #pragma unroll
;                 for (int m = 0; m < 4; ++m)
; #pragma unroll
;                     for (int n = 0; n < 2; ++n) acc[a][b][m][n] = (f32x4){0.f, 0.f, 0.f, 0.f};
.LBB0_2809:
	s_ashr_i32 s23, s22, 31
	s_lshl_b64 s[24:25], s[22:23], 21
	s_add_u32 s24, s30, s24
	s_addc_u32 s25, s31, s25
	s_and_b64 s[26:27], s[4:5], exec
	s_cselect_b32 s23, s25, s3
	s_cselect_b32 s53, s24, s2
	s_ashr_i32 s21, s20, 31
	s_lshl_b64 s[26:27], s[20:21], 21
	s_add_u32 s26, s35, s26
	s_addc_u32 s27, s41, s27
	s_and_b64 s[28:29], s[4:5], exec
	s_cselect_b32 s21, s27, s7
	s_cselect_b32 s54, s26, s6
	s_add_u32 s2, s2, 0x100080
	s_addc_u32 s3, s3, 0
	s_add_u32 s55, s6, 0x100
	v_mov_b32_e32 v0, 0
	s_addc_u32 s56, s7, 0
	s_mov_b32 s57, -2
	v_mov_b32_e32 v1, v0
	v_mov_b64_e32 v[2:3], 0
	v_mov_b64_e32 v[8:9], 0
	v_mov_b64_e32 v[10:11], 0
	v_mov_b64_e32 v[16:17], 0
	v_mov_b64_e32 v[18:19], 0
	v_mov_b64_e32 v[24:25], 0
	v_mov_b64_e32 v[26:27], 0
	v_mov_b64_e32 v[32:33], 0
	v_mov_b64_e32 v[34:35], 0
	v_mov_b64_e32 v[40:41], 0
	v_mov_b64_e32 v[42:43], 0
	v_mov_b64_e32 v[48:49], 0
	v_mov_b64_e32 v[50:51], 0
	v_mov_b64_e32 v[56:57], 0
	v_mov_b64_e32 v[58:59], 0
	v_mov_b64_e32 v[4:5], 0
	v_mov_b64_e32 v[6:7], 0
	v_mov_b64_e32 v[12:13], 0
	v_mov_b64_e32 v[14:15], 0
	v_mov_b64_e32 v[20:21], 0
	v_mov_b64_e32 v[22:23], 0
	v_mov_b64_e32 v[28:29], 0
	v_mov_b64_e32 v[30:31], 0
	v_mov_b64_e32 v[36:37], 0
	v_mov_b64_e32 v[38:39], 0
	v_mov_b64_e32 v[44:45], 0
	v_mov_b64_e32 v[46:47], 0
	v_mov_b64_e32 v[52:53], 0
	v_mov_b64_e32 v[54:55], 0
	v_mov_b64_e32 v[60:61], 0
	v_mov_b64_e32 v[62:63], 0
	v_mov_b64_e32 v[64:65], 0
	v_mov_b64_e32 v[66:67], 0
	v_mov_b64_e32 v[72:73], 0
	v_mov_b64_e32 v[74:75], 0
	v_mov_b64_e32 v[80:81], 0
	v_mov_b64_e32 v[82:83], 0
	v_mov_b64_e32 v[88:89], 0
	v_mov_b64_e32 v[90:91], 0
	v_mov_b64_e32 v[96:97], 0
	v_mov_b64_e32 v[98:99], 0
	v_mov_b64_e32 v[104:105], 0
	v_mov_b64_e32 v[106:107], 0
	v_mov_b64_e32 v[112:113], 0
	v_mov_b64_e32 v[114:115], 0
	v_mov_b64_e32 v[120:121], 0
	v_mov_b64_e32 v[122:123], 0
	v_mov_b64_e32 v[68:69], 0
	v_mov_b64_e32 v[70:71], 0
	v_mov_b64_e32 v[76:77], 0
	v_mov_b64_e32 v[78:79], 0
	v_mov_b64_e32 v[84:85], 0
	v_mov_b64_e32 v[86:87], 0
	v_mov_b64_e32 v[92:93], 0
	v_mov_b64_e32 v[94:95], 0
	v_mov_b64_e32 v[100:101], 0
	v_mov_b64_e32 v[102:103], 0
	v_mov_b64_e32 v[108:109], 0
	v_mov_b64_e32 v[110:111], 0
	v_mov_b64_e32 v[116:117], 0
	v_mov_b64_e32 v[118:119], 0
	v_mov_b64_e32 v[124:125], 0
	v_mov_b64_e32 v[126:127], 0

; template <class Epi, class Sched, bool ALIGN_EPI = false, bool SP2 = false>
; __device__ __forceinline__ void gemm_phase(PG8_LAS unsigned char* lds, const Gemm g, const Sched& S, const Epi& E, const int wid) {
;     ...
;         const char* nA = has_next ? (const char*)g.A + (size_t)nxt.pm * tstep : cA; const char* nB = has_next ? (const char*)g.Bt + (size_t)nxt.pn * tstep : cB;
;         for (int t = 0; t < nt; t += 2) {
;             const bool last = (t == nt - 2);
;             const char* a1 = cA + (size_t)(t + 1) * kstep;
;             const char* a2 = last ? nA : cA + (size_t)(t + 2) * kstep; const char* b2 = last ? nB : cB + (size_t)(t + 2) * kstep;
;     ...
; #pragma unroll
;         for (int a = 0; a < 2; ++a)
; #pragma unroll
;             for (int b = 0; b < 2; ++b)
; #pragma unroll
;                 for (int m = 0; m < 4; ++m)
; #pragma unroll
;                     for (int n = 0; n < 2; ++n) acc[a][b][m][n] = (f32x4){0.f, 0.f, 0.f, 0.f};
.LBB0_2825:
	s_ashr_i32 s23, s22, 31
	s_lshl_b64 s[24:25], s[22:23], 21
	s_add_u32 s24, s30, s24
	s_addc_u32 s25, s31, s25
	s_and_b64 s[26:27], s[4:5], exec
	s_cselect_b32 s23, s25, s3
	s_cselect_b32 s54, s24, s2
	s_ashr_i32 s21, s20, 31
	s_lshl_b64 s[26:27], s[20:21], 21
	s_add_u32 s26, s34, s26
	s_addc_u32 s27, s35, s27
	s_and_b64 s[28:29], s[4:5], exec
	s_cselect_b32 s21, s27, s7
	s_cselect_b32 s55, s26, s6
	s_add_u32 s2, s2, 0x100080
	s_addc_u32 s3, s3, 0
	s_add_u32 s56, s6, 0x100
	v_mov_b32_e32 v0, 0
	s_addc_u32 s57, s7, 0
	s_mov_b32 s58, -2
	v_mov_b32_e32 v1, v0
	v_mov_b64_e32 v[2:3], 0
	v_mov_b64_e32 v[8:9], 0
	v_mov_b64_e32 v[10:11], 0
	v_mov_b64_e32 v[16:17], 0
	v_mov_b64_e32 v[18:19], 0
	v_mov_b64_e32 v[24:25], 0
	v_mov_b64_e32 v[26:27], 0
	v_mov_b64_e32 v[32:33], 0
	v_mov_b64_e32 v[34:35], 0
	v_mov_b64_e32 v[40:41], 0
	v_mov_b64_e32 v[42:43], 0
	v_mov_b64_e32 v[48:49], 0
	v_mov_b64_e32 v[50:51], 0
	v_mov_b64_e32 v[56:57], 0
	v_mov_b64_e32 v[58:59], 0
	v_mov_b64_e32 v[4:5], 0
	v_mov_b64_e32 v[6:7], 0
	v_mov_b64_e32 v[12:13], 0
	v_mov_b64_e32 v[14:15], 0
	v_mov_b64_e32 v[20:21], 0
	v_mov_b64_e32 v[22:23], 0
	v_mov_b64_e32 v[28:29], 0
	v_mov_b64_e32 v[30:31], 0
	v_mov_b64_e32 v[36:37], 0
	v_mov_b64_e32 v[38:39], 0
	v_mov_b64_e32 v[44:45], 0
	v_mov_b64_e32 v[46:47], 0
	v_mov_b64_e32 v[52:53], 0
	v_mov_b64_e32 v[54:55], 0
	v_mov_b64_e32 v[60:61], 0
	v_mov_b64_e32 v[62:63], 0
	v_mov_b64_e32 v[64:65], 0
	v_mov_b64_e32 v[66:67], 0
	v_mov_b64_e32 v[72:73], 0
	v_mov_b64_e32 v[74:75], 0
	v_mov_b64_e32 v[80:81], 0
	v_mov_b64_e32 v[82:83], 0
	v_mov_b64_e32 v[88:89], 0
	v_mov_b64_e32 v[90:91], 0
	v_mov_b64_e32 v[96:97], 0
	v_mov_b64_e32 v[98:99], 0
	v_mov_b64_e32 v[104:105], 0
	v_mov_b64_e32 v[106:107], 0
	v_mov_b64_e32 v[112:113], 0
	v_mov_b64_e32 v[114:115], 0
	v_mov_b64_e32 v[120:121], 0
	v_mov_b64_e32 v[122:123], 0
	v_mov_b64_e32 v[68:69], 0
	v_mov_b64_e32 v[70:71], 0
	v_mov_b64_e32 v[76:77], 0
	v_mov_b64_e32 v[78:79], 0
	v_mov_b64_e32 v[84:85], 0
	v_mov_b64_e32 v[86:87], 0
	v_mov_b64_e32 v[92:93], 0
	v_mov_b64_e32 v[94:95], 0
	v_mov_b64_e32 v[100:101], 0
	v_mov_b64_e32 v[102:103], 0
	v_mov_b64_e32 v[108:109], 0
	v_mov_b64_e32 v[110:111], 0
	v_mov_b64_e32 v[116:117], 0
	v_mov_b64_e32 v[118:119], 0
	v_mov_b64_e32 v[124:125], 0
	v_mov_b64_e32 v[126:127], 0

;     DI bool next(int i, Unit& u) const { const int L = i * G + c; if (L >= 1536) return false; const int which = L >> 9, r = L & 511; u.pm = which * 64 + (r & 63); u.pn = which * 8 + (r >> 6); return true; }
;     DI bool next(int i, Unit& u) const { Unit t; if (!so.next(i >> 1, t)) return false; const int which = i & 1; u.pm = which * 64 + t.pm; u.pn = which * 16 + t.pn; return true; }
; template <class Epi, class Sched, bool ALIGN_EPI = false, bool SP2 = false>
; __device__ __forceinline__ void gemm_phase(PG8_LAS unsigned char* lds, const Gemm g, const Sched& S, const Epi& E, const int wid) {
;     ...
;     f32x4 acc[2][2][4][2];
; #pragma unroll
;     for (int a = 0; a < 2; ++a)
; #pragma unroll
;         for (int b = 0; b < 2; ++b)
; #pragma unroll
;             for (int m = 0; m < 4; ++m)
; #pragma unroll
;                 for (int n = 0; n < 2; ++n) acc[a][b][m][n] = (f32x4){0.f, 0.f, 0.f, 0.f};
;     ...
;     for (;;) {
;         const bool has_next = S.next(ui + 1, nxt);
;         const char* nA = has_next ? (const char*)g.A + (size_t)nxt.pm * tstep : cA; const char* nB = has_next ? (const char*)g.Bt + (size_t)nxt.pn * tstep : cB;
;         for (int t = 0; t < nt; t += 2) {
;             const bool last = (t == nt - 2);
;             const char* a1 = cA + (size_t)(t + 1) * kstep;
;             const char* a2 = last ? nA : cA + (size_t)(t + 2) * kstep; const char* b2 = last ? nB : cB + (size_t)(t + 2) * kstep;
;     ...
; #pragma unroll
;         for (int a = 0; a < 2; ++a)
; #pragma unroll
;             for (int b = 0; b < 2; ++b)
; #pragma unroll
;                 for (int m = 0; m < 4; ++m)
; #pragma unroll
;                     for (int n = 0; n < 2; ++n) acc[a][b][m][n] = (f32x4){0.f, 0.f, 0.f, 0.f};
.LBB0_2850:
	v_mov_b32_e32 v123, 0
	s_andn2_b64 vcc, exec, s[16:17]
	v_mov_b32_e32 v122, v123
	v_mov_b32_e32 v121, v123
	v_mov_b32_e32 v120, v123
	v_mov_b32_e32 v127, v123
	v_mov_b32_e32 v126, v123
	v_mov_b32_e32 v125, v123
	v_mov_b32_e32 v124, v123
	v_mov_b32_e32 v111, v123
	v_mov_b32_e32 v110, v123
	v_mov_b32_e32 v109, v123
	v_mov_b32_e32 v108, v123
	v_mov_b32_e32 v107, v123
	v_mov_b32_e32 v106, v123
	v_mov_b32_e32 v105, v123
	v_mov_b32_e32 v104, v123
	v_mov_b32_e32 v95, v123
	v_mov_b32_e32 v94, v123
	v_mov_b32_e32 v93, v123
	v_mov_b32_e32 v92, v123
	v_mov_b32_e32 v91, v123
	v_mov_b32_e32 v90, v123
	v_mov_b32_e32 v89, v123
	v_mov_b32_e32 v88, v123
	v_mov_b32_e32 v79, v123
	v_mov_b32_e32 v78, v123
	v_mov_b32_e32 v77, v123
	v_mov_b32_e32 v76, v123
	v_mov_b32_e32 v75, v123
	v_mov_b32_e32 v74, v123
	v_mov_b32_e32 v73, v123
	v_mov_b32_e32 v72, v123
	v_mov_b32_e32 v119, v123
	v_mov_b32_e32 v118, v123
	v_mov_b32_e32 v117, v123
	v_mov_b32_e32 v116, v123
	v_mov_b32_e32 v115, v123
	v_mov_b32_e32 v114, v123
	v_mov_b32_e32 v113, v123
	v_mov_b32_e32 v112, v123
	v_mov_b32_e32 v103, v123
	v_mov_b32_e32 v102, v123
	v_mov_b32_e32 v101, v123
	v_mov_b32_e32 v100, v123
	v_mov_b32_e32 v99, v123
	v_mov_b32_e32 v98, v123
	v_mov_b32_e32 v97, v123
	v_mov_b32_e32 v96, v123
	v_mov_b32_e32 v87, v123
	v_mov_b32_e32 v86, v123
	v_mov_b32_e32 v85, v123
	v_mov_b32_e32 v84, v123
	v_mov_b32_e32 v83, v123
	v_mov_b32_e32 v82, v123
	v_mov_b32_e32 v81, v123
	v_mov_b32_e32 v80, v123
	v_mov_b32_e32 v71, v123
	v_mov_b32_e32 v70, v123
	v_mov_b32_e32 v69, v123
	v_mov_b32_e32 v68, v123
	v_mov_b32_e32 v67, v123
	v_mov_b32_e32 v66, v123
	v_mov_b32_e32 v65, v123
	v_mov_b32_e32 v64, v123
	v_mov_b32_e32 v63, v123
	v_mov_b32_e32 v62, v123
	v_mov_b32_e32 v61, v123
	v_mov_b32_e32 v60, v123
	v_mov_b32_e32 v59, v123
	v_mov_b32_e32 v58, v123
	v_mov_b32_e32 v57, v123
	v_mov_b32_e32 v56, v123
	v_mov_b32_e32 v47, v123
	v_mov_b32_e32 v46, v123
	v_mov_b32_e32 v45, v123
	v_mov_b32_e32 v44, v123
	v_mov_b32_e32 v43, v123
	v_mov_b32_e32 v42, v123
	v_mov_b32_e32 v41, v123
	v_mov_b32_e32 v40, v123
	v_mov_b32_e32 v31, v123
	v_mov_b32_e32 v30, v123
	v_mov_b32_e32 v29, v123
	v_mov_b32_e32 v28, v123
	v_mov_b32_e32 v27, v123
	v_mov_b32_e32 v26, v123
	v_mov_b32_e32 v25, v123
	v_mov_b32_e32 v24, v123
	v_mov_b32_e32 v15, v123
	v_mov_b32_e32 v14, v123
	v_mov_b32_e32 v13, v123
	v_mov_b32_e32 v12, v123
	v_mov_b32_e32 v11, v123
	v_mov_b32_e32 v10, v123
	v_mov_b32_e32 v9, v123
	v_mov_b32_e32 v8, v123
	v_mov_b32_e32 v55, v123
	v_mov_b32_e32 v54, v123
	v_mov_b32_e32 v53, v123
	v_mov_b32_e32 v52, v123
	v_mov_b32_e32 v51, v123
	v_mov_b32_e32 v50, v123
	v_mov_b32_e32 v49, v123
	v_mov_b32_e32 v48, v123
	v_mov_b32_e32 v39, v123
	v_mov_b32_e32 v38, v123
	v_mov_b32_e32 v37, v123
	v_mov_b32_e32 v36, v123
	v_mov_b32_e32 v35, v123
	v_mov_b32_e32 v34, v123
	v_mov_b32_e32 v33, v123
	v_mov_b32_e32 v32, v123
	v_mov_b32_e32 v23, v123
	v_mov_b32_e32 v22, v123
	v_mov_b32_e32 v21, v123
	v_mov_b32_e32 v20, v123
	v_mov_b32_e32 v19, v123
	v_mov_b32_e32 v18, v123
	v_mov_b32_e32 v17, v123
	v_mov_b32_e32 v16, v123
	v_mov_b32_e32 v7, v123
	v_mov_b32_e32 v6, v123
	v_mov_b32_e32 v5, v123
	v_mov_b32_e32 v4, v123
	v_mov_b32_e32 v3, v123
	v_mov_b32_e32 v2, v123
	v_mov_b32_e32 v1, v123
	v_mov_b32_e32 v0, v123
	s_cbranch_vccnz .LBB0_2853
	s_add_u32 s30, s30, 0x80
	s_addc_u32 s31, s31, 0
	s_add_u32 s63, s34, 0x100
	v_mov_b32_e32 v0, 0
	s_addc_u32 s64, s35, 0
	s_mov_b32 s34, 0
	v_mov_b32_e32 v1, v0
	v_mov_b64_e32 v[2:3], 0
	v_mov_b64_e32 v[4:5], 0
	v_mov_b64_e32 v[6:7], 0
	v_mov_b64_e32 v[16:17], 0
	v_mov_b64_e32 v[18:19], 0
	v_mov_b64_e32 v[20:21], 0
	v_mov_b64_e32 v[22:23], 0
	v_mov_b64_e32 v[32:33], 0
	v_mov_b64_e32 v[34:35], 0
	v_mov_b64_e32 v[36:37], 0
	v_mov_b64_e32 v[38:39], 0
	v_mov_b64_e32 v[48:49], 0
	v_mov_b64_e32 v[50:51], 0
	v_mov_b64_e32 v[52:53], 0
	v_mov_b64_e32 v[54:55], 0
	v_mov_b64_e32 v[8:9], 0
	v_mov_b64_e32 v[10:11], 0
	v_mov_b64_e32 v[12:13], 0
	v_mov_b64_e32 v[14:15], 0
	v_mov_b64_e32 v[24:25], 0
	v_mov_b64_e32 v[26:27], 0
	v_mov_b64_e32 v[28:29], 0
	v_mov_b64_e32 v[30:31], 0
	v_mov_b64_e32 v[40:41], 0
	v_mov_b64_e32 v[42:43], 0
	v_mov_b64_e32 v[44:45], 0
	v_mov_b64_e32 v[46:47], 0
	v_mov_b64_e32 v[56:57], 0
	v_mov_b64_e32 v[58:59], 0
	v_mov_b64_e32 v[60:61], 0
	v_mov_b64_e32 v[62:63], 0
	v_mov_b64_e32 v[64:65], 0
	v_mov_b64_e32 v[66:67], 0
	v_mov_b64_e32 v[68:69], 0
	v_mov_b64_e32 v[70:71], 0
	v_mov_b64_e32 v[80:81], 0
	v_mov_b64_e32 v[82:83], 0
	v_mov_b64_e32 v[84:85], 0
	v_mov_b64_e32 v[86:87], 0
	v_mov_b64_e32 v[96:97], 0
	v_mov_b64_e32 v[98:99], 0
	v_mov_b64_e32 v[100:101], 0
	v_mov_b64_e32 v[102:103], 0
	v_mov_b64_e32 v[112:113], 0
	v_mov_b64_e32 v[114:115], 0
	v_mov_b64_e32 v[116:117], 0
	v_mov_b64_e32 v[118:119], 0
	v_mov_b64_e32 v[72:73], 0
	v_mov_b64_e32 v[74:75], 0
	v_mov_b64_e32 v[76:77], 0
	v_mov_b64_e32 v[78:79], 0
	v_mov_b64_e32 v[88:89], 0
	v_mov_b64_e32 v[90:91], 0
	v_mov_b64_e32 v[92:93], 0
	v_mov_b64_e32 v[94:95], 0
	v_mov_b64_e32 v[104:105], 0
	v_mov_b64_e32 v[106:107], 0
	v_mov_b64_e32 v[108:109], 0
	v_mov_b64_e32 v[110:111], 0
	v_mov_b64_e32 v[124:125], 0
	v_mov_b64_e32 v[126:127], 0
	v_mov_b64_e32 v[120:121], 0
	v_mov_b64_e32 v[122:123], 0

; template <class Epi, class Sched, bool ALIGN_EPI = false, bool SP2 = false>
; __device__ __forceinline__ void gemm_phase(PG8_LAS unsigned char* lds, const Gemm g, const Sched& S, const Epi& E, const int wid) {
;     ...
;         const char* nA = has_next ? (const char*)g.A + (size_t)nxt.pm * tstep : cA; const char* nB = has_next ? (const char*)g.Bt + (size_t)nxt.pn * tstep : cB;
;         for (int t = 0; t < nt; t += 2) {
;             const bool last = (t == nt - 2);
;             const char* a1 = cA + (size_t)(t + 1) * kstep;
;             const char* a2 = last ? nA : cA + (size_t)(t + 2) * kstep; const char* b2 = last ? nB : cB + (size_t)(t + 2) * kstep;
;     ...
; #pragma unroll
;         for (int a = 0; a < 2; ++a)
; #pragma unroll
;             for (int b = 0; b < 2; ++b)
; #pragma unroll
;                 for (int m = 0; m < 4; ++m)
; #pragma unroll
;                     for (int n = 0; n < 2; ++n) acc[a][b][m][n] = (f32x4){0.f, 0.f, 0.f, 0.f};
.LBB0_2934:
	s_add_u32 s51, s24, 0x100
	v_mov_b32_e32 v0, 0
	s_addc_u32 s52, s25, 0
	s_mov_b32 s53, -2
	s_waitcnt lgkmcnt(0)
	v_mov_b32_e32 v1, v0
	v_mov_b64_e32 v[2:3], 0
	v_mov_b64_e32 v[4:5], 0
	v_mov_b64_e32 v[6:7], 0
	v_mov_b64_e32 v[16:17], 0
	v_mov_b64_e32 v[18:19], 0
	v_mov_b64_e32 v[20:21], 0
	v_mov_b64_e32 v[22:23], 0
	v_mov_b64_e32 v[32:33], 0
	v_mov_b64_e32 v[34:35], 0
	v_mov_b64_e32 v[36:37], 0
	v_mov_b64_e32 v[38:39], 0
	v_mov_b64_e32 v[48:49], 0
	v_mov_b64_e32 v[50:51], 0
	v_mov_b64_e32 v[52:53], 0
	v_mov_b64_e32 v[54:55], 0
	v_mov_b64_e32 v[8:9], 0
	v_mov_b64_e32 v[10:11], 0
	v_mov_b64_e32 v[12:13], 0
	v_mov_b64_e32 v[14:15], 0
	v_mov_b64_e32 v[24:25], 0
	v_mov_b64_e32 v[26:27], 0
	v_mov_b64_e32 v[28:29], 0
	v_mov_b64_e32 v[30:31], 0
	v_mov_b64_e32 v[40:41], 0
	v_mov_b64_e32 v[42:43], 0
	v_mov_b64_e32 v[44:45], 0
	v_mov_b64_e32 v[46:47], 0
	v_mov_b64_e32 v[56:57], 0
	v_mov_b64_e32 v[58:59], 0
	v_mov_b64_e32 v[60:61], 0
	v_mov_b64_e32 v[62:63], 0
	v_mov_b64_e32 v[64:65], 0
	v_mov_b64_e32 v[66:67], 0
	v_mov_b64_e32 v[68:69], 0
	v_mov_b64_e32 v[70:71], 0
	v_mov_b64_e32 v[80:81], 0
	v_mov_b64_e32 v[82:83], 0
	v_mov_b64_e32 v[84:85], 0
	v_mov_b64_e32 v[86:87], 0
	v_mov_b64_e32 v[96:97], 0
	v_mov_b64_e32 v[98:99], 0
	v_mov_b64_e32 v[100:101], 0
	v_mov_b64_e32 v[102:103], 0
	v_mov_b64_e32 v[112:113], 0
	v_mov_b64_e32 v[114:115], 0
	v_mov_b64_e32 v[116:117], 0
	v_mov_b64_e32 v[118:119], 0
	v_mov_b64_e32 v[72:73], 0
	v_mov_b64_e32 v[74:75], 0
	v_mov_b64_e32 v[76:77], 0
	v_mov_b64_e32 v[78:79], 0
	v_mov_b64_e32 v[88:89], 0
	v_mov_b64_e32 v[90:91], 0
	v_mov_b64_e32 v[92:93], 0
	v_mov_b64_e32 v[94:95], 0
	v_mov_b64_e32 v[104:105], 0
	v_mov_b64_e32 v[106:107], 0
	v_mov_b64_e32 v[108:109], 0
	v_mov_b64_e32 v[110:111], 0
	v_mov_b64_e32 v[120:121], 0
	v_mov_b64_e32 v[122:123], 0
	v_mov_b64_e32 v[124:125], 0
	v_mov_b64_e32 v[126:127], 0

; template <class Epi, class Sched, bool ALIGN_EPI = false, bool SP2 = false>
; __device__ __forceinline__ void gemm_phase(PG8_LAS unsigned char* lds, const Gemm g, const Sched& S, const Epi& E, const int wid) {
;     ...
;         const char* nA = has_next ? (const char*)g.A + (size_t)nxt.pm * tstep : cA; const char* nB = has_next ? (const char*)g.Bt + (size_t)nxt.pn * tstep : cB;
;         for (int t = 0; t < nt; t += 2) {
;             const bool last = (t == nt - 2);
;             const char* a1 = cA + (size_t)(t + 1) * kstep;
;             const char* a2 = last ? nA : cA + (size_t)(t + 2) * kstep; const char* b2 = last ? nB : cB + (size_t)(t + 2) * kstep;
;     ...
; #pragma unroll
;         for (int a = 0; a < 2; ++a)
; #pragma unroll
;             for (int b = 0; b < 2; ++b)
; #pragma unroll
;                 for (int m = 0; m < 4; ++m)
; #pragma unroll
;                     for (int n = 0; n < 2; ++n) acc[a][b][m][n] = (f32x4){0.f, 0.f, 0.f, 0.f};
.LBB0_3029:
	s_ashr_i32 s27, s26, 31
	s_lshl_b64 s[28:29], s[26:27], 21
	s_add_u32 s28, s8, s28
	s_addc_u32 s29, s9, s29
	s_and_b64 s[30:31], s[4:5], exec
	s_cselect_b32 s1, s29, s35
	s_cselect_b32 s7, s28, s34
	s_ashr_i32 s25, s24, 31
	s_lshl_b64 s[30:31], s[24:25], 21
	s_add_u32 s30, s33, s30
	s_addc_u32 s31, s40, s31
	s_and_b64 s[38:39], s[4:5], exec
	s_cselect_b32 s25, s31, s37
	s_cselect_b32 s27, s30, s36
	s_add_u32 s34, s34, 0x100080
	s_addc_u32 s35, s35, 0
	s_add_u32 s55, s36, 0x100
	v_mov_b32_e32 v0, 0
	s_addc_u32 s56, s37, 0
	s_mov_b32 s57, -2
	s_waitcnt lgkmcnt(0)
	v_mov_b32_e32 v1, v0
	v_mov_b64_e32 v[2:3], 0
	v_mov_b64_e32 v[4:5], 0
	v_mov_b64_e32 v[6:7], 0
	v_mov_b64_e32 v[16:17], 0
	v_mov_b64_e32 v[18:19], 0
	v_mov_b64_e32 v[20:21], 0
	v_mov_b64_e32 v[22:23], 0
	v_mov_b64_e32 v[32:33], 0
	v_mov_b64_e32 v[34:35], 0
	v_mov_b64_e32 v[36:37], 0
	v_mov_b64_e32 v[38:39], 0
	v_mov_b64_e32 v[48:49], 0
	v_mov_b64_e32 v[50:51], 0
	v_mov_b64_e32 v[52:53], 0
	v_mov_b64_e32 v[54:55], 0
	v_mov_b64_e32 v[8:9], 0
	v_mov_b64_e32 v[10:11], 0
	v_mov_b64_e32 v[12:13], 0
	v_mov_b64_e32 v[14:15], 0
	v_mov_b64_e32 v[24:25], 0
	v_mov_b64_e32 v[26:27], 0
	v_mov_b64_e32 v[28:29], 0
	v_mov_b64_e32 v[30:31], 0
	v_mov_b64_e32 v[40:41], 0
	v_mov_b64_e32 v[42:43], 0
	v_mov_b64_e32 v[44:45], 0
	v_mov_b64_e32 v[46:47], 0
	v_mov_b64_e32 v[56:57], 0
	v_mov_b64_e32 v[58:59], 0
	v_mov_b64_e32 v[60:61], 0
	v_mov_b64_e32 v[62:63], 0
	v_mov_b64_e32 v[64:65], 0
	v_mov_b64_e32 v[66:67], 0
	v_mov_b64_e32 v[68:69], 0
	v_mov_b64_e32 v[70:71], 0
	v_mov_b64_e32 v[80:81], 0
	v_mov_b64_e32 v[82:83], 0
	v_mov_b64_e32 v[84:85], 0
	v_mov_b64_e32 v[86:87], 0
	v_mov_b64_e32 v[96:97], 0
	v_mov_b64_e32 v[98:99], 0
	v_mov_b64_e32 v[100:101], 0
	v_mov_b64_e32 v[102:103], 0
	v_mov_b64_e32 v[112:113], 0
	v_mov_b64_e32 v[114:115], 0
	v_mov_b64_e32 v[116:117], 0
	v_mov_b64_e32 v[118:119], 0
	v_mov_b64_e32 v[72:73], 0
	v_mov_b64_e32 v[74:75], 0
	v_mov_b64_e32 v[76:77], 0
	v_mov_b64_e32 v[78:79], 0
	v_mov_b64_e32 v[88:89], 0
	v_mov_b64_e32 v[90:91], 0
	v_mov_b64_e32 v[92:93], 0
	v_mov_b64_e32 v[94:95], 0
	v_mov_b64_e32 v[104:105], 0
	v_mov_b64_e32 v[106:107], 0
	v_mov_b64_e32 v[108:109], 0
	v_mov_b64_e32 v[110:111], 0
	v_mov_b64_e32 v[120:121], 0
	v_mov_b64_e32 v[122:123], 0
	v_mov_b64_e32 v[124:125], 0
	v_mov_b64_e32 v[126:127], 0
